# mixer-in/LoRA and residual GEMM loops: first K-iteration peeled, first MFMA of each accumulator takes C=0, accumulator zero fill removed
# speedup vs baseline: 1.0194x; 1.0028x over previous
; #define PG8_STAGE(bufoff, gbase, voff) do { _Pragma("unroll") for (int _i = 0; _i < 2; ++_i) \
;         __builtin_amdgcn_global_load_lds((const unsigned*)((const char*)(gbase) + (voff)[_i]), (PG8_LAS unsigned*)(lds + (bufoff) + ldsw + _i * 8192), 16, 0, 0); } while (0)
; #define PG8_LDA(dst, b, h) do { _Pragma("unroll") for (int m = 0; m < 4; ++m) _Pragma("unroll") for (int k = 0; k < 2; ++k) dst[m][k] = *(const PG8_LAS bf16x8*)(lds + PG8_SA(b, h) + aoff + m * 2048 + k * 1024); } while (0)
; #define PG8_LDB(dst, b, h) do { _Pragma("unroll") for (int n = 0; n < 2; ++n) _Pragma("unroll") for (int k = 0; k < 2; ++k) dst[n][k] = *(const PG8_LAS bf16x8*)(lds + PG8_SB(b, h) + boff + n * 2048 + k * 1024); } while (0)
; #define PG8_MMA(ai, bj, At, Bt) do { __builtin_amdgcn_s_setprio(1); _Pragma("unroll") for (int m = 0; m < 4; ++m) _Pragma("unroll") for (int n = 0; n < 2; ++n) _Pragma("unroll") for (int k = 0; k < 2; ++k) \
;         acc[ai][bj][m][n] = __builtin_amdgcn_mfma_f32_16x16x32_bf16(Bt[n][k], At[m][k], acc[ai][bj][m][n], 0, 0, 0); __builtin_amdgcn_s_setprio(0); } while (0)
; #define PG8_WAIT_V(n) asm volatile("s_waitcnt vmcnt(" #n ")" ::: "memory")
; #define PG8_WAIT_L(n) asm volatile("s_waitcnt lgkmcnt(" #n ")" ::: "memory")
; #define PG8_BAR __builtin_amdgcn_s_barrier()
; #define PG8_SCHED __builtin_amdgcn_sched_barrier(0)
; template <class Epi, class Sched, bool ALIGN_EPI = false, bool SP2 = false>
; __device__ __forceinline__ void gemm_phase(PG8_LAS unsigned char* lds, const Gemm g, const Sched& S, const Epi& E, const int tid_) {
;     ...
;             const bool last = (t == nt - 2);
;             const char* a1 = cA + (size_t)(t + 1) * kstep;
;             const char* a2 = last ? nA : cA + (size_t)(t + 2) * kstep; const char* b2 = last ? nB : cB + (size_t)(t + 2) * kstep;
;             const char* a3 = a2 + kstep; const char* b3 = b2 + kstep;
;             if (last && has_next) S.a_ready(nxt);
;             if constexpr (SP2) {
;             PG8_LDB(B0, 0, 0); PG8_LDB(B1, 0, 1); PG8_SCHED; PG8_LDA(At, 0, 0); PG8_STAGE(PG8_SA(1, 1), a1 + hstep, voffA);
;             PG8_WAIT_V(8); PG8_WAIT_L(0); PG8_BAR; PG8_MMA(0, 0, At, B0); PG8_MMA(0, 1, At, B1); PG8_BAR; PG8_SCHED;
;             PG8_LDA(At, 0, 1); PG8_STAGE(PG8_SB(0, 0), b2, voffB); PG8_STAGE(PG8_SB(0, 1), b2 + hstepB, voffB); PG8_STAGE(PG8_SA(0, 0), a2, voffA);
.LBB0_368:
	s_add_u32 s8, s52, 0x80
	s_addc_u32 s9, s53, 0
	s_add_u32 s2, s12, 0x100
	s_addc_u32 s3, s13, 0
	s_mov_b32 s10, 0
	s_waitcnt lgkmcnt(0)
	v_add_u32_e32 v40, s61, v197
	v_add_u32_e32 v160, s64, v197
	ds_read_b128 v[12:15], v40
	ds_read_b128 v[16:19], v40 offset:1024
	ds_read_b128 v[36:39], v40 offset:2048
	ds_read_b128 v[40:43], v40 offset:3072
	ds_read_b128 v[148:151], v160
	ds_read_b128 v[152:155], v160 offset:1024
	ds_read_b128 v[156:159], v160 offset:2048
	ds_read_b128 v[160:163], v160 offset:3072
	s_add_i32 s12, s10, 2
	s_add_u32 s13, s8, 0x80
	s_addc_u32 s11, s9, 0
	s_cmp_eq_u32 s82, s10
	s_cselect_b32 s10, s48, s13
	s_cselect_b32 s11, s49, s11
	s_cselect_b32 s53, s51, s3
	s_cselect_b32 s52, s50, s2
	v_lshl_add_u64 v[194:195], s[8:9], 0, v[190:191]
	s_add_i32 m0, s67, 0xc000
	ds_read_b128 v[164:167], v238
	ds_read_b128 v[168:171], v238 offset:1024
	ds_read_b128 v[198:201], v238 offset:2048
	ds_read_b128 v[202:205], v238 offset:3072
	ds_read_b128 v[206:209], v238 offset:4096
	ds_read_b128 v[210:213], v238 offset:5120
	ds_read_b128 v[214:217], v238 offset:6144
	ds_read_b128 v[218:221], v238 offset:7168
	global_load_lds_dwordx4 v[194:195], off
	v_lshl_add_u64 v[194:195], s[8:9], 0, v[192:193]
	s_add_i32 m0, s67, 0xe000
	s_nop 0
	global_load_lds_dwordx4 v[194:195], off
	s_waitcnt vmcnt(8)
	s_waitcnt lgkmcnt(0)
	s_barrier
	s_setprio 1
	s_waitcnt lgkmcnt(0)
	v_mfma_f32_16x16x32_bf16 v[144:147], v[12:15], v[164:167], 0
	v_mfma_f32_16x16x32_bf16 v[140:143], v[36:39], v[164:167], 0
	v_mfma_f32_16x16x32_bf16 v[128:131], v[12:15], v[198:201], 0
	v_mfma_f32_16x16x32_bf16 v[124:127], v[36:39], v[198:201], 0
	v_mfma_f32_16x16x32_bf16 v[112:115], v[12:15], v[206:209], 0
	v_mfma_f32_16x16x32_bf16 v[108:111], v[36:39], v[206:209], 0
	v_mfma_f32_16x16x32_bf16 v[96:99], v[12:15], v[214:217], 0
	v_mfma_f32_16x16x32_bf16 v[92:95], v[36:39], v[214:217], 0
	v_mfma_f32_16x16x32_bf16 v[144:147], v[16:19], v[168:171], v[144:147]
	v_mfma_f32_16x16x32_bf16 v[140:143], v[40:43], v[168:171], v[140:143]
	v_mfma_f32_16x16x32_bf16 v[128:131], v[16:19], v[202:205], v[128:131]
	v_mfma_f32_16x16x32_bf16 v[124:127], v[40:43], v[202:205], v[124:127]
	v_mfma_f32_16x16x32_bf16 v[112:115], v[16:19], v[210:213], v[112:115]
	v_mfma_f32_16x16x32_bf16 v[108:111], v[40:43], v[210:213], v[108:111]
	v_mfma_f32_16x16x32_bf16 v[96:99], v[16:19], v[218:221], v[96:99]
	v_mfma_f32_16x16x32_bf16 v[92:95], v[40:43], v[218:221], v[92:95]
	s_setprio 0
	s_setprio 1
	v_mfma_f32_16x16x32_bf16 v[136:139], v[148:151], v[164:167], 0
	v_mfma_f32_16x16x32_bf16 v[132:135], v[156:159], v[164:167], 0
	v_mfma_f32_16x16x32_bf16 v[120:123], v[148:151], v[198:201], 0
	v_mfma_f32_16x16x32_bf16 v[116:119], v[156:159], v[198:201], 0
	v_mfma_f32_16x16x32_bf16 v[104:107], v[148:151], v[206:209], 0
	v_mfma_f32_16x16x32_bf16 v[100:103], v[156:159], v[206:209], 0
	v_mfma_f32_16x16x32_bf16 v[88:91], v[148:151], v[214:217], 0
	v_mfma_f32_16x16x32_bf16 v[84:87], v[156:159], v[214:217], 0
	v_mfma_f32_16x16x32_bf16 v[136:139], v[152:155], v[168:171], v[136:139]
	v_mfma_f32_16x16x32_bf16 v[132:135], v[160:163], v[168:171], v[132:135]
	v_mfma_f32_16x16x32_bf16 v[120:123], v[152:155], v[202:205], v[120:123]
	v_mfma_f32_16x16x32_bf16 v[116:119], v[160:163], v[202:205], v[116:119]
	v_mfma_f32_16x16x32_bf16 v[104:107], v[152:155], v[210:213], v[104:107]
	v_mfma_f32_16x16x32_bf16 v[100:103], v[160:163], v[210:213], v[100:103]
	v_mfma_f32_16x16x32_bf16 v[88:91], v[152:155], v[218:221], v[88:91]
	v_mfma_f32_16x16x32_bf16 v[84:87], v[160:163], v[218:221], v[84:87]
	s_setprio 0
	s_barrier
	s_mov_b32 m0, s62
	v_lshl_add_u64 v[194:195], s[52:53], 0, v[172:173]
	v_lshl_add_u64 v[222:223], s[52:53], 0, v[176:177]
	s_add_u32 s52, s52, s38
	ds_read_b128 v[164:167], v238 offset:16384
	ds_read_b128 v[168:171], v238 offset:17408
	ds_read_b128 v[198:201], v238 offset:18432
	ds_read_b128 v[202:205], v238 offset:19456
	ds_read_b128 v[206:209], v238 offset:20480
	ds_read_b128 v[210:213], v238 offset:21504
	ds_read_b128 v[214:217], v238 offset:22528
	ds_read_b128 v[218:221], v238 offset:23552
	global_load_lds_dwordx4 v[194:195], off
	s_mov_b32 m0, s63
	s_addc_u32 s53, s53, s39
	global_load_lds_dwordx4 v[222:223], off
	v_lshl_add_u64 v[224:225], s[52:53], 0, v[172:173]
	s_mov_b32 m0, s65
	v_lshl_add_u64 v[226:227], s[52:53], 0, v[176:177]
	global_load_lds_dwordx4 v[224:225], off
	s_mov_b32 m0, s66
	v_lshl_add_u64 v[228:229], s[10:11], 0, v[0:1]
	global_load_lds_dwordx4 v[226:227], off
	s_mov_b32 m0, s67
	v_lshl_add_u64 v[230:231], s[10:11], 0, v[174:175]
	global_load_lds_dwordx4 v[228:229], off
	s_mov_b32 m0, s68
	s_nop 0
	global_load_lds_dwordx4 v[230:231], off
	s_waitcnt vmcnt(8)
	s_waitcnt lgkmcnt(0)
	s_barrier
; #define PG8_STAGE(bufoff, gbase, voff) do { _Pragma("unroll") for (int _i = 0; _i < 2; ++_i) \
;         __builtin_amdgcn_global_load_lds((const unsigned*)((const char*)(gbase) + (voff)[_i]), (PG8_LAS unsigned*)(lds + (bufoff) + ldsw + _i * 8192), 16, 0, 0); } while (0)
; #define PG8_LDA(dst, b, h) do { _Pragma("unroll") for (int m = 0; m < 4; ++m) _Pragma("unroll") for (int k = 0; k < 2; ++k) dst[m][k] = *(const PG8_LAS bf16x8*)(lds + PG8_SA(b, h) + aoff + m * 2048 + k * 1024); } while (0)
; #define PG8_LDB(dst, b, h) do { _Pragma("unroll") for (int n = 0; n < 2; ++n) _Pragma("unroll") for (int k = 0; k < 2; ++k) dst[n][k] = *(const PG8_LAS bf16x8*)(lds + PG8_SB(b, h) + boff + n * 2048 + k * 1024); } while (0)
; #define PG8_MMA(ai, bj, At, Bt) do { __builtin_amdgcn_s_setprio(1); _Pragma("unroll") for (int m = 0; m < 4; ++m) _Pragma("unroll") for (int n = 0; n < 2; ++n) _Pragma("unroll") for (int k = 0; k < 2; ++k) \
;         acc[ai][bj][m][n] = __builtin_amdgcn_mfma_f32_16x16x32_bf16(Bt[n][k], At[m][k], acc[ai][bj][m][n], 0, 0, 0); __builtin_amdgcn_s_setprio(0); } while (0)
; #define PG8_WAIT_V(n) asm volatile("s_waitcnt vmcnt(" #n ")" ::: "memory")
; #define PG8_WAIT_L(n) asm volatile("s_waitcnt lgkmcnt(" #n ")" ::: "memory")
; #define PG8_BAR __builtin_amdgcn_s_barrier()
; #define PG8_SCHED __builtin_amdgcn_sched_barrier(0)
; template <class Epi, class Sched, bool ALIGN_EPI = false, bool SP2 = false>
; __device__ __forceinline__ void gemm_phase(PG8_LAS unsigned char* lds, const Gemm g, const Sched& S, const Epi& E, const int tid_) {
;     ...
;             PG8_WAIT_V(8); PG8_WAIT_L(0); PG8_BAR; PG8_MMA(1, 0, At, B0); PG8_MMA(1, 1, At, B1); PG8_BAR; PG8_SCHED;
;             PG8_LDB(B0, 1, 0); PG8_LDB(B1, 1, 1); PG8_SCHED; PG8_LDA(At, 1, 0); PG8_STAGE(PG8_SA(0, 1), a2 + hstep, voffA);
;             PG8_WAIT_V(8); PG8_WAIT_L(0); PG8_BAR; PG8_MMA(0, 0, At, B0); PG8_MMA(0, 1, At, B1); PG8_BAR; PG8_SCHED;
	s_setprio 1
	s_waitcnt lgkmcnt(0)
	v_mfma_f32_16x16x32_bf16 v[80:83], v[12:15], v[164:167], 0
	v_mfma_f32_16x16x32_bf16 v[76:79], v[36:39], v[164:167], 0
	v_mfma_f32_16x16x32_bf16 v[64:67], v[12:15], v[198:201], 0
	v_mfma_f32_16x16x32_bf16 v[60:63], v[36:39], v[198:201], 0
	v_mfma_f32_16x16x32_bf16 v[48:51], v[12:15], v[206:209], 0
	v_mfma_f32_16x16x32_bf16 v[44:47], v[36:39], v[206:209], 0
	v_mfma_f32_16x16x32_bf16 v[12:15], v[12:15], v[214:217], 0
	v_mfma_f32_16x16x32_bf16 v[80:83], v[16:19], v[168:171], v[80:83]
	v_mfma_f32_16x16x32_bf16 v[76:79], v[40:43], v[168:171], v[76:79]
	v_mfma_f32_16x16x32_bf16 v[64:67], v[16:19], v[202:205], v[64:67]
	v_mfma_f32_16x16x32_bf16 v[60:63], v[40:43], v[202:205], v[60:63]
	v_mfma_f32_16x16x32_bf16 v[48:51], v[16:19], v[210:213], v[48:51]
	v_mfma_f32_16x16x32_bf16 v[44:47], v[40:43], v[210:213], v[44:47]
	v_mfma_f32_16x16x32_bf16 v[12:15], v[16:19], v[218:221], v[12:15]
	v_mfma_f32_16x16x32_bf16 v[16:19], v[36:39], v[214:217], 0
	v_mfma_f32_16x16x32_bf16 v[16:19], v[40:43], v[218:221], v[16:19]
	s_setprio 0
	s_setprio 1
	v_mfma_f32_16x16x32_bf16 v[20:23], v[148:151], v[164:167], 0
	v_mfma_f32_16x16x32_bf16 v[36:39], v[152:155], v[168:171], v[20:23]
	v_mfma_f32_16x16x32_bf16 v[20:23], v[156:159], v[164:167], 0
	v_mfma_f32_16x16x32_bf16 v[40:43], v[160:163], v[168:171], v[20:23]
	v_mfma_f32_16x16x32_bf16 v[20:23], v[148:151], v[198:201], 0
	v_mfma_f32_16x16x32_bf16 v[56:59], v[152:155], v[202:205], v[20:23]
	v_mfma_f32_16x16x32_bf16 v[20:23], v[156:159], v[198:201], 0
	v_mfma_f32_16x16x32_bf16 v[52:55], v[160:163], v[202:205], v[20:23]
	v_mfma_f32_16x16x32_bf16 v[20:23], v[148:151], v[206:209], 0
	v_mfma_f32_16x16x32_bf16 v[32:35], v[152:155], v[210:213], v[20:23]
	v_mfma_f32_16x16x32_bf16 v[20:23], v[156:159], v[206:209], 0
	v_mfma_f32_16x16x32_bf16 v[8:11], v[148:151], v[214:217], 0
	v_mfma_f32_16x16x32_bf16 v[4:7], v[156:159], v[214:217], 0
	v_mfma_f32_16x16x32_bf16 v[28:31], v[160:163], v[210:213], v[20:23]
	v_mfma_f32_16x16x32_bf16 v[8:11], v[152:155], v[218:221], v[8:11]
	v_mfma_f32_16x16x32_bf16 v[4:7], v[160:163], v[218:221], v[4:7]
	s_setprio 0
	s_barrier
	v_add_u32_e32 v72, s71, v197
	v_add_u32_e32 v160, s76, v197
	ds_read_b128 v[20:23], v72
	ds_read_b128 v[24:27], v72 offset:1024
	ds_read_b128 v[68:71], v72 offset:2048
	ds_read_b128 v[72:75], v72 offset:3072
	ds_read_b128 v[148:151], v160
	ds_read_b128 v[152:155], v160 offset:1024
	ds_read_b128 v[156:159], v160 offset:2048
	ds_read_b128 v[160:163], v160 offset:3072
	s_add_u32 s10, s10, s34
	s_addc_u32 s11, s11, s35
	s_mov_b32 m0, s69
	v_lshl_add_u64 v[232:233], s[10:11], 0, v[0:1]
	ds_read_b128 v[164:167], v238 offset:32768
	ds_read_b128 v[168:171], v238 offset:33792
	ds_read_b128 v[198:201], v238 offset:34816
	ds_read_b128 v[202:205], v238 offset:35840
	ds_read_b128 v[206:209], v238 offset:36864
	ds_read_b128 v[210:213], v238 offset:37888
	ds_read_b128 v[214:217], v238 offset:38912
	ds_read_b128 v[218:221], v238 offset:39936
	global_load_lds_dwordx4 v[232:233], off
	v_lshl_add_u64 v[232:233], s[10:11], 0, v[174:175]
	s_mov_b32 m0, s70
	s_nop 0
	global_load_lds_dwordx4 v[232:233], off
	s_waitcnt vmcnt(8)
	s_waitcnt lgkmcnt(0)
	s_barrier
	s_setprio 1
	s_waitcnt lgkmcnt(0)
	v_mfma_f32_16x16x32_bf16 v[144:147], v[20:23], v[164:167], v[144:147]
	v_mfma_f32_16x16x32_bf16 v[140:143], v[68:71], v[164:167], v[140:143]
	v_mfma_f32_16x16x32_bf16 v[128:131], v[20:23], v[198:201], v[128:131]
	v_mfma_f32_16x16x32_bf16 v[124:127], v[68:71], v[198:201], v[124:127]
	v_mfma_f32_16x16x32_bf16 v[112:115], v[20:23], v[206:209], v[112:115]
	v_mfma_f32_16x16x32_bf16 v[108:111], v[68:71], v[206:209], v[108:111]
	v_mfma_f32_16x16x32_bf16 v[96:99], v[20:23], v[214:217], v[96:99]
	v_mfma_f32_16x16x32_bf16 v[92:95], v[68:71], v[214:217], v[92:95]
	v_mfma_f32_16x16x32_bf16 v[144:147], v[24:27], v[168:171], v[144:147]
	v_mfma_f32_16x16x32_bf16 v[140:143], v[72:75], v[168:171], v[140:143]
	v_mfma_f32_16x16x32_bf16 v[128:131], v[24:27], v[202:205], v[128:131]
	v_mfma_f32_16x16x32_bf16 v[124:127], v[72:75], v[202:205], v[124:127]
	v_mfma_f32_16x16x32_bf16 v[112:115], v[24:27], v[210:213], v[112:115]
	v_mfma_f32_16x16x32_bf16 v[108:111], v[72:75], v[210:213], v[108:111]
	v_mfma_f32_16x16x32_bf16 v[96:99], v[24:27], v[218:221], v[96:99]
	v_mfma_f32_16x16x32_bf16 v[92:95], v[72:75], v[218:221], v[92:95]
	s_setprio 0
	s_setprio 1
	v_mfma_f32_16x16x32_bf16 v[136:139], v[148:151], v[164:167], v[136:139]
	v_mfma_f32_16x16x32_bf16 v[132:135], v[156:159], v[164:167], v[132:135]
	v_mfma_f32_16x16x32_bf16 v[120:123], v[148:151], v[198:201], v[120:123]
	v_mfma_f32_16x16x32_bf16 v[116:119], v[156:159], v[198:201], v[116:119]
	v_mfma_f32_16x16x32_bf16 v[104:107], v[148:151], v[206:209], v[104:107]
	v_mfma_f32_16x16x32_bf16 v[100:103], v[156:159], v[206:209], v[100:103]
	v_mfma_f32_16x16x32_bf16 v[88:91], v[148:151], v[214:217], v[88:91]
	v_mfma_f32_16x16x32_bf16 v[84:87], v[156:159], v[214:217], v[84:87]
	v_mfma_f32_16x16x32_bf16 v[136:139], v[152:155], v[168:171], v[136:139]
	v_mfma_f32_16x16x32_bf16 v[132:135], v[160:163], v[168:171], v[132:135]
	v_mfma_f32_16x16x32_bf16 v[120:123], v[152:155], v[202:205], v[120:123]
	v_mfma_f32_16x16x32_bf16 v[116:119], v[160:163], v[202:205], v[116:119]
	v_mfma_f32_16x16x32_bf16 v[104:107], v[152:155], v[210:213], v[104:107]
	v_mfma_f32_16x16x32_bf16 v[100:103], v[160:163], v[210:213], v[100:103]
	v_mfma_f32_16x16x32_bf16 v[88:91], v[152:155], v[218:221], v[88:91]
	v_mfma_f32_16x16x32_bf16 v[84:87], v[160:163], v[218:221], v[84:87]
	s_setprio 0
	s_barrier
; #define PG8_STAGE(bufoff, gbase, voff) do { _Pragma("unroll") for (int _i = 0; _i < 2; ++_i) \
;         __builtin_amdgcn_global_load_lds((const unsigned*)((const char*)(gbase) + (voff)[_i]), (PG8_LAS unsigned*)(lds + (bufoff) + ldsw + _i * 8192), 16, 0, 0); } while (0)
; #define PG8_LDA(dst, b, h) do { _Pragma("unroll") for (int m = 0; m < 4; ++m) _Pragma("unroll") for (int k = 0; k < 2; ++k) dst[m][k] = *(const PG8_LAS bf16x8*)(lds + PG8_SA(b, h) + aoff + m * 2048 + k * 1024); } while (0)
; #define PG8_MMA(ai, bj, At, Bt) do { __builtin_amdgcn_s_setprio(1); _Pragma("unroll") for (int m = 0; m < 4; ++m) _Pragma("unroll") for (int n = 0; n < 2; ++n) _Pragma("unroll") for (int k = 0; k < 2; ++k) \
;         acc[ai][bj][m][n] = __builtin_amdgcn_mfma_f32_16x16x32_bf16(Bt[n][k], At[m][k], acc[ai][bj][m][n], 0, 0, 0); __builtin_amdgcn_s_setprio(0); } while (0)
; #define PG8_WAIT_V(n) asm volatile("s_waitcnt vmcnt(" #n ")" ::: "memory")
; #define PG8_WAIT_L(n) asm volatile("s_waitcnt lgkmcnt(" #n ")" ::: "memory")
; #define PG8_BAR __builtin_amdgcn_s_barrier()
; #define PG8_SCHED __builtin_amdgcn_sched_barrier(0)
; template <class Epi, class Sched, bool ALIGN_EPI = false, bool SP2 = false>
; __device__ __forceinline__ void gemm_phase(PG8_LAS unsigned char* lds, const Gemm g, const Sched& S, const Epi& E, const int tid_) {
;     ...
;         for (int t = 0; t < nt; t += 2) {
;     ...
;             PG8_LDA(At, 1, 1); PG8_STAGE(PG8_SB(1, 0), b3, voffB); PG8_STAGE(PG8_SB(1, 1), b3 + hstepB, voffB); PG8_STAGE(PG8_SA(1, 0), a3, voffA);
;             PG8_WAIT_V(8); PG8_WAIT_L(0); PG8_BAR; PG8_MMA(1, 0, At, B0); PG8_MMA(1, 1, At, B1); PG8_BAR; PG8_SCHED;
	s_mov_b32 m0, s72
	v_lshl_add_u64 v[194:195], v[194:195], 0, s[96:97]
	ds_read_b128 v[164:167], v238 offset:49152
	ds_read_b128 v[168:171], v238 offset:50176
	ds_read_b128 v[198:201], v238 offset:51200
	ds_read_b128 v[202:205], v238 offset:52224
	ds_read_b128 v[206:209], v238 offset:53248
	ds_read_b128 v[210:213], v238 offset:54272
	ds_read_b128 v[214:217], v238 offset:55296
	ds_read_b128 v[218:221], v238 offset:56320
	global_load_lds_dwordx4 v[194:195], off
	v_lshl_add_u64 v[194:195], v[222:223], 0, s[96:97]
	s_mov_b32 m0, s73
	s_nop 0
	global_load_lds_dwordx4 v[194:195], off
	v_lshl_add_u64 v[194:195], v[224:225], 0, s[96:97]
	s_mov_b32 m0, s77
	s_nop 0
	global_load_lds_dwordx4 v[194:195], off
	v_lshl_add_u64 v[194:195], v[226:227], 0, s[96:97]
	s_mov_b32 m0, s80
	s_nop 0
	global_load_lds_dwordx4 v[194:195], off
	v_lshl_add_u64 v[194:195], v[228:229], 0, s[96:97]
	s_mov_b32 m0, s74
	s_nop 0
	global_load_lds_dwordx4 v[194:195], off
	v_lshl_add_u64 v[194:195], v[230:231], 0, s[96:97]
	s_mov_b32 m0, s75
	s_nop 0
	global_load_lds_dwordx4 v[194:195], off
	s_waitcnt vmcnt(8)
	s_waitcnt lgkmcnt(0)
	s_barrier
	s_setprio 1
	s_waitcnt lgkmcnt(0)
	v_mfma_f32_16x16x32_bf16 v[80:83], v[20:23], v[164:167], v[80:83]
	v_mfma_f32_16x16x32_bf16 v[64:67], v[20:23], v[198:201], v[64:67]
	v_mfma_f32_16x16x32_bf16 v[48:51], v[20:23], v[206:209], v[48:51]
	v_mfma_f32_16x16x32_bf16 v[12:15], v[20:23], v[214:217], v[12:15]
	v_mfma_f32_16x16x32_bf16 v[80:83], v[24:27], v[168:171], v[80:83]
	v_mfma_f32_16x16x32_bf16 v[76:79], v[68:71], v[164:167], v[76:79]
	v_mfma_f32_16x16x32_bf16 v[64:67], v[24:27], v[202:205], v[64:67]
	v_mfma_f32_16x16x32_bf16 v[60:63], v[68:71], v[198:201], v[60:63]
	v_mfma_f32_16x16x32_bf16 v[48:51], v[24:27], v[210:213], v[48:51]
	v_mfma_f32_16x16x32_bf16 v[44:47], v[68:71], v[206:209], v[44:47]
	v_mfma_f32_16x16x32_bf16 v[24:27], v[24:27], v[218:221], v[12:15]
	v_mfma_f32_16x16x32_bf16 v[12:15], v[68:71], v[214:217], v[16:19]
	v_mfma_f32_16x16x32_bf16 v[76:79], v[72:75], v[168:171], v[76:79]
	v_mfma_f32_16x16x32_bf16 v[60:63], v[72:75], v[202:205], v[60:63]
	v_mfma_f32_16x16x32_bf16 v[44:47], v[72:75], v[210:213], v[44:47]
	v_mfma_f32_16x16x32_bf16 v[20:23], v[72:75], v[218:221], v[12:15]
	s_setprio 0
	s_setprio 1
	v_mfma_f32_16x16x32_bf16 v[12:15], v[148:151], v[164:167], v[36:39]
	v_mfma_f32_16x16x32_bf16 v[72:75], v[152:155], v[168:171], v[12:15]
	v_mfma_f32_16x16x32_bf16 v[12:15], v[156:159], v[164:167], v[40:43]
	v_mfma_f32_16x16x32_bf16 v[68:71], v[160:163], v[168:171], v[12:15]
	v_mfma_f32_16x16x32_bf16 v[12:15], v[148:151], v[198:201], v[56:59]
	v_mfma_f32_16x16x32_bf16 v[56:59], v[152:155], v[202:205], v[12:15]
	v_mfma_f32_16x16x32_bf16 v[12:15], v[156:159], v[198:201], v[52:55]
	v_mfma_f32_16x16x32_bf16 v[52:55], v[160:163], v[202:205], v[12:15]
	v_mfma_f32_16x16x32_bf16 v[12:15], v[148:151], v[206:209], v[32:35]
	v_mfma_f32_16x16x32_bf16 v[32:35], v[152:155], v[210:213], v[12:15]
	v_mfma_f32_16x16x32_bf16 v[12:15], v[156:159], v[206:209], v[28:31]
	v_mfma_f32_16x16x32_bf16 v[8:11], v[148:151], v[214:217], v[8:11]
	v_mfma_f32_16x16x32_bf16 v[4:7], v[156:159], v[214:217], v[4:7]
	v_mfma_f32_16x16x32_bf16 v[28:31], v[160:163], v[210:213], v[12:15]
	v_mfma_f32_16x16x32_bf16 v[8:11], v[152:155], v[218:221], v[8:11]
	v_mfma_f32_16x16x32_bf16 v[4:7], v[160:163], v[218:221], v[4:7]
	s_setprio 0
	s_barrier
	s_add_u32 s8, s8, 0x100
	s_addc_u32 s9, s9, 0
	s_add_u32 s2, s2, 0x100
	s_addc_u32 s3, s3, 0
	s_cmp_ge_u32 s12, s81
	s_mov_b32 s10, s12

; #define PG8_STAGE(bufoff, gbase, voff) do { _Pragma("unroll") for (int _i = 0; _i < 2; ++_i) \
;         __builtin_amdgcn_global_load_lds((const unsigned*)((const char*)(gbase) + (voff)[_i]), (PG8_LAS unsigned*)(lds + (bufoff) + ldsw + _i * 8192), 16, 0, 0); } while (0)
; #define PG8_LDA(dst, b, h) do { _Pragma("unroll") for (int m = 0; m < 4; ++m) _Pragma("unroll") for (int k = 0; k < 2; ++k) dst[m][k] = *(const PG8_LAS bf16x8*)(lds + PG8_SA(b, h) + aoff + m * 2048 + k * 1024); } while (0)
; #define PG8_LDB(dst, b, h) do { _Pragma("unroll") for (int n = 0; n < 2; ++n) _Pragma("unroll") for (int k = 0; k < 2; ++k) dst[n][k] = *(const PG8_LAS bf16x8*)(lds + PG8_SB(b, h) + boff + n * 2048 + k * 1024); } while (0)
; #define PG8_MMA(ai, bj, At, Bt) do { __builtin_amdgcn_s_setprio(1); _Pragma("unroll") for (int m = 0; m < 4; ++m) _Pragma("unroll") for (int n = 0; n < 2; ++n) _Pragma("unroll") for (int k = 0; k < 2; ++k) \
;         acc[ai][bj][m][n] = __builtin_amdgcn_mfma_f32_16x16x32_bf16(Bt[n][k], At[m][k], acc[ai][bj][m][n], 0, 0, 0); __builtin_amdgcn_s_setprio(0); } while (0)
; #define PG8_WAIT_V(n) asm volatile("s_waitcnt vmcnt(" #n ")" ::: "memory")
; #define PG8_WAIT_L(n) asm volatile("s_waitcnt lgkmcnt(" #n ")" ::: "memory")
; #define PG8_BAR __builtin_amdgcn_s_barrier()
; #define PG8_SCHED __builtin_amdgcn_sched_barrier(0)
; template <class Epi, class Sched, bool ALIGN_EPI = false, bool SP2 = false>
; __device__ __forceinline__ void gemm_phase(PG8_LAS unsigned char* lds, const Gemm g, const Sched& S, const Epi& E, const int tid_) {
;     ...
;             const bool last = (t == nt - 2);
;             const char* a1 = cA + (size_t)(t + 1) * kstep;
;             const char* a2 = last ? nA : cA + (size_t)(t + 2) * kstep; const char* b2 = last ? nB : cB + (size_t)(t + 2) * kstep;
;             const char* a3 = a2 + kstep; const char* b3 = b2 + kstep;
;             if (last && has_next) S.a_ready(nxt);
;             if constexpr (SP2) {
;             PG8_LDB(B0, 0, 0); PG8_LDB(B1, 0, 1); PG8_SCHED; PG8_LDA(At, 0, 0); PG8_STAGE(PG8_SA(1, 1), a1 + hstep, voffA);
;             PG8_WAIT_V(8); PG8_WAIT_L(0); PG8_BAR; PG8_MMA(0, 0, At, B0); PG8_MMA(0, 1, At, B1); PG8_BAR; PG8_SCHED;
;             PG8_LDA(At, 0, 1); PG8_STAGE(PG8_SB(0, 0), b2, voffB); PG8_STAGE(PG8_SB(0, 1), b2 + hstepB, voffB); PG8_STAGE(PG8_SA(0, 0), a2, voffA);
.LBB0_527:
	s_add_u32 s12, s48, 0x80
	s_addc_u32 s13, s49, 0
	s_add_u32 s2, s46, 0x100
	s_addc_u32 s3, s47, 0
	s_mov_b32 s14, 0
	s_waitcnt lgkmcnt(0)
	v_add_u32_e32 v56, s53, v214
	v_add_u32_e32 v160, s56, v214
	ds_read_b128 v[36:39], v56
	ds_read_b128 v[40:43], v56 offset:1024
	ds_read_b128 v[48:51], v56 offset:2048
	ds_read_b128 v[56:59], v56 offset:3072
	ds_read_b128 v[148:151], v160
	ds_read_b128 v[152:155], v160 offset:1024
	ds_read_b128 v[156:159], v160 offset:2048
	ds_read_b128 v[160:163], v160 offset:3072
	s_add_i32 s46, s14, 2
	s_add_u32 s47, s12, 0x80
	s_addc_u32 s15, s13, 0
	s_cmp_eq_u32 s74, s14
	s_cselect_b32 s14, s42, s47
	s_cselect_b32 s15, s43, s15
	s_cselect_b32 s49, s45, s3
	s_cselect_b32 s48, s44, s2
	v_lshl_add_u64 v[212:213], s[12:13], 0, v[192:193]
	s_add_i32 m0, s59, 0xc000
	ds_read_b128 v[164:167], v216
	ds_read_b128 v[168:171], v216 offset:1024
	ds_read_b128 v[172:175], v216 offset:2048
	ds_read_b128 v[176:179], v216 offset:3072
	ds_read_b128 v[196:199], v216 offset:4096
	ds_read_b128 v[200:203], v216 offset:5120
	ds_read_b128 v[204:207], v216 offset:6144
	ds_read_b128 v[208:211], v216 offset:7168
	global_load_lds_dwordx4 v[212:213], off
	v_lshl_add_u64 v[212:213], s[12:13], 0, v[194:195]
	s_add_i32 m0, s59, 0xe000
	s_nop 0
	global_load_lds_dwordx4 v[212:213], off
	s_waitcnt vmcnt(8)
	s_waitcnt lgkmcnt(0)
	s_barrier
	s_setprio 1
	s_waitcnt lgkmcnt(0)
	v_mfma_f32_16x16x32_bf16 v[144:147], v[36:39], v[164:167], 0
	v_mfma_f32_16x16x32_bf16 v[140:143], v[48:51], v[164:167], 0
	v_mfma_f32_16x16x32_bf16 v[128:131], v[36:39], v[172:175], 0
	v_mfma_f32_16x16x32_bf16 v[124:127], v[48:51], v[172:175], 0
	v_mfma_f32_16x16x32_bf16 v[112:115], v[36:39], v[196:199], 0
	v_mfma_f32_16x16x32_bf16 v[108:111], v[48:51], v[196:199], 0
	v_mfma_f32_16x16x32_bf16 v[96:99], v[36:39], v[204:207], 0
	v_mfma_f32_16x16x32_bf16 v[92:95], v[48:51], v[204:207], 0
	v_mfma_f32_16x16x32_bf16 v[144:147], v[40:43], v[168:171], v[144:147]
	v_mfma_f32_16x16x32_bf16 v[140:143], v[56:59], v[168:171], v[140:143]
	v_mfma_f32_16x16x32_bf16 v[128:131], v[40:43], v[176:179], v[128:131]
	v_mfma_f32_16x16x32_bf16 v[124:127], v[56:59], v[176:179], v[124:127]
	v_mfma_f32_16x16x32_bf16 v[112:115], v[40:43], v[200:203], v[112:115]
	v_mfma_f32_16x16x32_bf16 v[108:111], v[56:59], v[200:203], v[108:111]
	v_mfma_f32_16x16x32_bf16 v[96:99], v[40:43], v[208:211], v[96:99]
	v_mfma_f32_16x16x32_bf16 v[92:95], v[56:59], v[208:211], v[92:95]
	s_setprio 0
	s_setprio 1
	v_mfma_f32_16x16x32_bf16 v[136:139], v[148:151], v[164:167], 0
	v_mfma_f32_16x16x32_bf16 v[132:135], v[156:159], v[164:167], 0
	v_mfma_f32_16x16x32_bf16 v[120:123], v[148:151], v[172:175], 0
	v_mfma_f32_16x16x32_bf16 v[116:119], v[156:159], v[172:175], 0
	v_mfma_f32_16x16x32_bf16 v[104:107], v[148:151], v[196:199], 0
	v_mfma_f32_16x16x32_bf16 v[100:103], v[156:159], v[196:199], 0
	v_mfma_f32_16x16x32_bf16 v[88:91], v[148:151], v[204:207], 0
	v_mfma_f32_16x16x32_bf16 v[84:87], v[156:159], v[204:207], 0
	v_mfma_f32_16x16x32_bf16 v[136:139], v[152:155], v[168:171], v[136:139]
	v_mfma_f32_16x16x32_bf16 v[132:135], v[160:163], v[168:171], v[132:135]
	v_mfma_f32_16x16x32_bf16 v[120:123], v[152:155], v[176:179], v[120:123]
	v_mfma_f32_16x16x32_bf16 v[116:119], v[160:163], v[176:179], v[116:119]
	v_mfma_f32_16x16x32_bf16 v[104:107], v[152:155], v[200:203], v[104:107]
	v_mfma_f32_16x16x32_bf16 v[100:103], v[160:163], v[200:203], v[100:103]
	v_mfma_f32_16x16x32_bf16 v[88:91], v[152:155], v[208:211], v[88:91]
	v_mfma_f32_16x16x32_bf16 v[84:87], v[160:163], v[208:211], v[84:87]
	s_setprio 0
	s_barrier
	s_mov_b32 m0, s54
	v_lshl_add_u64 v[212:213], s[48:49], 0, v[2:3]
	v_lshl_add_u64 v[218:219], s[48:49], 0, v[190:191]
	s_add_u32 s48, s48, s52
	ds_read_b128 v[164:167], v216 offset:16384
	ds_read_b128 v[168:171], v216 offset:17408
	ds_read_b128 v[172:175], v216 offset:18432
	ds_read_b128 v[176:179], v216 offset:19456
	ds_read_b128 v[196:199], v216 offset:20480
	ds_read_b128 v[200:203], v216 offset:21504
	ds_read_b128 v[204:207], v216 offset:22528
	ds_read_b128 v[208:211], v216 offset:23552
	global_load_lds_dwordx4 v[212:213], off
	s_mov_b32 m0, s55
	s_addc_u32 s49, s49, 0
	global_load_lds_dwordx4 v[218:219], off
	v_lshl_add_u64 v[220:221], s[48:49], 0, v[2:3]
	s_mov_b32 m0, s57
	v_lshl_add_u64 v[222:223], s[48:49], 0, v[190:191]
	global_load_lds_dwordx4 v[220:221], off
	s_mov_b32 m0, s58
	v_lshl_add_u64 v[224:225], s[14:15], 0, v[0:1]
	global_load_lds_dwordx4 v[222:223], off
	s_mov_b32 m0, s59
	v_lshl_add_u64 v[226:227], s[14:15], 0, v[188:189]
	global_load_lds_dwordx4 v[224:225], off
	s_mov_b32 m0, s60
	s_nop 0
	global_load_lds_dwordx4 v[226:227], off
	s_waitcnt vmcnt(8)
	s_waitcnt lgkmcnt(0)
	s_barrier
; #define PG8_STAGE(bufoff, gbase, voff) do { _Pragma("unroll") for (int _i = 0; _i < 2; ++_i) \
;         __builtin_amdgcn_global_load_lds((const unsigned*)((const char*)(gbase) + (voff)[_i]), (PG8_LAS unsigned*)(lds + (bufoff) + ldsw + _i * 8192), 16, 0, 0); } while (0)
; #define PG8_LDA(dst, b, h) do { _Pragma("unroll") for (int m = 0; m < 4; ++m) _Pragma("unroll") for (int k = 0; k < 2; ++k) dst[m][k] = *(const PG8_LAS bf16x8*)(lds + PG8_SA(b, h) + aoff + m * 2048 + k * 1024); } while (0)
; #define PG8_LDB(dst, b, h) do { _Pragma("unroll") for (int n = 0; n < 2; ++n) _Pragma("unroll") for (int k = 0; k < 2; ++k) dst[n][k] = *(const PG8_LAS bf16x8*)(lds + PG8_SB(b, h) + boff + n * 2048 + k * 1024); } while (0)
; #define PG8_MMA(ai, bj, At, Bt) do { __builtin_amdgcn_s_setprio(1); _Pragma("unroll") for (int m = 0; m < 4; ++m) _Pragma("unroll") for (int n = 0; n < 2; ++n) _Pragma("unroll") for (int k = 0; k < 2; ++k) \
;         acc[ai][bj][m][n] = __builtin_amdgcn_mfma_f32_16x16x32_bf16(Bt[n][k], At[m][k], acc[ai][bj][m][n], 0, 0, 0); __builtin_amdgcn_s_setprio(0); } while (0)
; #define PG8_WAIT_V(n) asm volatile("s_waitcnt vmcnt(" #n ")" ::: "memory")
; #define PG8_WAIT_L(n) asm volatile("s_waitcnt lgkmcnt(" #n ")" ::: "memory")
; #define PG8_BAR __builtin_amdgcn_s_barrier()
; #define PG8_SCHED __builtin_amdgcn_sched_barrier(0)
; template <class Epi, class Sched, bool ALIGN_EPI = false, bool SP2 = false>
; __device__ __forceinline__ void gemm_phase(PG8_LAS unsigned char* lds, const Gemm g, const Sched& S, const Epi& E, const int tid_) {
;     ...
;             PG8_WAIT_V(8); PG8_WAIT_L(0); PG8_BAR; PG8_MMA(1, 0, At, B0); PG8_MMA(1, 1, At, B1); PG8_BAR; PG8_SCHED;
;             PG8_LDB(B0, 1, 0); PG8_LDB(B1, 1, 1); PG8_SCHED; PG8_LDA(At, 1, 0); PG8_STAGE(PG8_SA(0, 1), a2 + hstep, voffA);
;             PG8_WAIT_V(8); PG8_WAIT_L(0); PG8_BAR; PG8_MMA(0, 0, At, B0); PG8_MMA(0, 1, At, B1); PG8_BAR; PG8_SCHED;
	s_setprio 1
	s_waitcnt lgkmcnt(0)
	v_mfma_f32_16x16x32_bf16 v[80:83], v[36:39], v[164:167], 0
	v_mfma_f32_16x16x32_bf16 v[76:79], v[48:51], v[164:167], 0
	v_mfma_f32_16x16x32_bf16 v[64:67], v[36:39], v[172:175], 0
	v_mfma_f32_16x16x32_bf16 v[60:63], v[48:51], v[172:175], 0
	v_mfma_f32_16x16x32_bf16 v[32:35], v[36:39], v[196:199], 0
	v_mfma_f32_16x16x32_bf16 v[28:31], v[48:51], v[196:199], 0
	v_mfma_f32_16x16x32_bf16 v[16:19], v[36:39], v[204:207], 0
	v_mfma_f32_16x16x32_bf16 v[12:15], v[48:51], v[204:207], 0
	v_mfma_f32_16x16x32_bf16 v[80:83], v[40:43], v[168:171], v[80:83]
	v_mfma_f32_16x16x32_bf16 v[76:79], v[56:59], v[168:171], v[76:79]
	v_mfma_f32_16x16x32_bf16 v[64:67], v[40:43], v[176:179], v[64:67]
	v_mfma_f32_16x16x32_bf16 v[60:63], v[56:59], v[176:179], v[60:63]
	v_mfma_f32_16x16x32_bf16 v[32:35], v[40:43], v[200:203], v[32:35]
	v_mfma_f32_16x16x32_bf16 v[28:31], v[56:59], v[200:203], v[28:31]
	v_mfma_f32_16x16x32_bf16 v[16:19], v[40:43], v[208:211], v[16:19]
	v_mfma_f32_16x16x32_bf16 v[12:15], v[56:59], v[208:211], v[12:15]
	s_setprio 0
	s_setprio 1
	v_mfma_f32_16x16x32_bf16 v[44:47], v[156:159], v[172:175], 0
	v_mfma_f32_16x16x32_bf16 v[24:27], v[148:151], v[196:199], 0
	v_mfma_f32_16x16x32_bf16 v[20:23], v[156:159], v[196:199], 0
	v_mfma_f32_16x16x32_bf16 v[8:11], v[148:151], v[204:207], 0
	v_mfma_f32_16x16x32_bf16 v[4:7], v[156:159], v[204:207], 0
	v_mfma_f32_16x16x32_bf16 v[36:39], v[148:151], v[164:167], 0
	v_mfma_f32_16x16x32_bf16 v[40:43], v[156:159], v[164:167], 0
	v_mfma_f32_16x16x32_bf16 v[48:51], v[148:151], v[172:175], 0
	v_mfma_f32_16x16x32_bf16 v[44:47], v[160:163], v[176:179], v[44:47]
	v_mfma_f32_16x16x32_bf16 v[24:27], v[152:155], v[200:203], v[24:27]
	v_mfma_f32_16x16x32_bf16 v[20:23], v[160:163], v[200:203], v[20:23]
	v_mfma_f32_16x16x32_bf16 v[8:11], v[152:155], v[208:211], v[8:11]
	v_mfma_f32_16x16x32_bf16 v[4:7], v[160:163], v[208:211], v[4:7]
	v_mfma_f32_16x16x32_bf16 v[36:39], v[152:155], v[168:171], v[36:39]
	v_mfma_f32_16x16x32_bf16 v[40:43], v[160:163], v[168:171], v[40:43]
	v_mfma_f32_16x16x32_bf16 v[48:51], v[152:155], v[176:179], v[48:51]
	s_setprio 0
	s_barrier
	v_add_u32_e32 v72, s63, v214
	v_add_u32_e32 v160, s68, v214
	ds_read_b128 v[52:55], v72
	ds_read_b128 v[56:59], v72 offset:1024
	ds_read_b128 v[68:71], v72 offset:2048
	ds_read_b128 v[72:75], v72 offset:3072
	ds_read_b128 v[148:151], v160
	ds_read_b128 v[152:155], v160 offset:1024
	ds_read_b128 v[156:159], v160 offset:2048
	ds_read_b128 v[160:163], v160 offset:3072
	s_add_u32 s14, s14, s24
	s_addc_u32 s15, s15, 0
	s_mov_b32 m0, s61
	v_lshl_add_u64 v[228:229], s[14:15], 0, v[0:1]
	ds_read_b128 v[164:167], v216 offset:32768
	ds_read_b128 v[168:171], v216 offset:33792
	ds_read_b128 v[172:175], v216 offset:34816
	ds_read_b128 v[176:179], v216 offset:35840
	ds_read_b128 v[196:199], v216 offset:36864
	ds_read_b128 v[200:203], v216 offset:37888
	ds_read_b128 v[204:207], v216 offset:38912
	ds_read_b128 v[208:211], v216 offset:39936
	global_load_lds_dwordx4 v[228:229], off
	v_lshl_add_u64 v[228:229], s[14:15], 0, v[188:189]
	s_mov_b32 m0, s62
	s_nop 0
	global_load_lds_dwordx4 v[228:229], off
	s_waitcnt vmcnt(8)
	s_waitcnt lgkmcnt(0)
	s_barrier
	s_setprio 1
	s_waitcnt lgkmcnt(0)
	v_mfma_f32_16x16x32_bf16 v[144:147], v[52:55], v[164:167], v[144:147]
	v_mfma_f32_16x16x32_bf16 v[140:143], v[68:71], v[164:167], v[140:143]
	v_mfma_f32_16x16x32_bf16 v[128:131], v[52:55], v[172:175], v[128:131]
	v_mfma_f32_16x16x32_bf16 v[124:127], v[68:71], v[172:175], v[124:127]
	v_mfma_f32_16x16x32_bf16 v[112:115], v[52:55], v[196:199], v[112:115]
	v_mfma_f32_16x16x32_bf16 v[108:111], v[68:71], v[196:199], v[108:111]
	v_mfma_f32_16x16x32_bf16 v[96:99], v[52:55], v[204:207], v[96:99]
	v_mfma_f32_16x16x32_bf16 v[92:95], v[68:71], v[204:207], v[92:95]
	v_mfma_f32_16x16x32_bf16 v[144:147], v[56:59], v[168:171], v[144:147]
	v_mfma_f32_16x16x32_bf16 v[140:143], v[72:75], v[168:171], v[140:143]
	v_mfma_f32_16x16x32_bf16 v[128:131], v[56:59], v[176:179], v[128:131]
	v_mfma_f32_16x16x32_bf16 v[124:127], v[72:75], v[176:179], v[124:127]
	v_mfma_f32_16x16x32_bf16 v[112:115], v[56:59], v[200:203], v[112:115]
	v_mfma_f32_16x16x32_bf16 v[108:111], v[72:75], v[200:203], v[108:111]
	v_mfma_f32_16x16x32_bf16 v[96:99], v[56:59], v[208:211], v[96:99]
	v_mfma_f32_16x16x32_bf16 v[92:95], v[72:75], v[208:211], v[92:95]
	s_setprio 0
	s_setprio 1
	v_mfma_f32_16x16x32_bf16 v[136:139], v[148:151], v[164:167], v[136:139]
	v_mfma_f32_16x16x32_bf16 v[132:135], v[156:159], v[164:167], v[132:135]
	v_mfma_f32_16x16x32_bf16 v[120:123], v[148:151], v[172:175], v[120:123]
	v_mfma_f32_16x16x32_bf16 v[116:119], v[156:159], v[172:175], v[116:119]
	v_mfma_f32_16x16x32_bf16 v[104:107], v[148:151], v[196:199], v[104:107]
	v_mfma_f32_16x16x32_bf16 v[100:103], v[156:159], v[196:199], v[100:103]
	v_mfma_f32_16x16x32_bf16 v[88:91], v[148:151], v[204:207], v[88:91]
	v_mfma_f32_16x16x32_bf16 v[84:87], v[156:159], v[204:207], v[84:87]
	v_mfma_f32_16x16x32_bf16 v[136:139], v[152:155], v[168:171], v[136:139]
	v_mfma_f32_16x16x32_bf16 v[132:135], v[160:163], v[168:171], v[132:135]
	v_mfma_f32_16x16x32_bf16 v[120:123], v[152:155], v[176:179], v[120:123]
	v_mfma_f32_16x16x32_bf16 v[116:119], v[160:163], v[176:179], v[116:119]
	v_mfma_f32_16x16x32_bf16 v[104:107], v[152:155], v[200:203], v[104:107]
	v_mfma_f32_16x16x32_bf16 v[100:103], v[160:163], v[200:203], v[100:103]
	v_mfma_f32_16x16x32_bf16 v[88:91], v[152:155], v[208:211], v[88:91]
	v_mfma_f32_16x16x32_bf16 v[84:87], v[160:163], v[208:211], v[84:87]
	s_setprio 0
	s_barrier
; #define PG8_STAGE(bufoff, gbase, voff) do { _Pragma("unroll") for (int _i = 0; _i < 2; ++_i) \
;         __builtin_amdgcn_global_load_lds((const unsigned*)((const char*)(gbase) + (voff)[_i]), (PG8_LAS unsigned*)(lds + (bufoff) + ldsw + _i * 8192), 16, 0, 0); } while (0)
; #define PG8_LDA(dst, b, h) do { _Pragma("unroll") for (int m = 0; m < 4; ++m) _Pragma("unroll") for (int k = 0; k < 2; ++k) dst[m][k] = *(const PG8_LAS bf16x8*)(lds + PG8_SA(b, h) + aoff + m * 2048 + k * 1024); } while (0)
; #define PG8_MMA(ai, bj, At, Bt) do { __builtin_amdgcn_s_setprio(1); _Pragma("unroll") for (int m = 0; m < 4; ++m) _Pragma("unroll") for (int n = 0; n < 2; ++n) _Pragma("unroll") for (int k = 0; k < 2; ++k) \
;         acc[ai][bj][m][n] = __builtin_amdgcn_mfma_f32_16x16x32_bf16(Bt[n][k], At[m][k], acc[ai][bj][m][n], 0, 0, 0); __builtin_amdgcn_s_setprio(0); } while (0)
; #define PG8_WAIT_V(n) asm volatile("s_waitcnt vmcnt(" #n ")" ::: "memory")
; #define PG8_WAIT_L(n) asm volatile("s_waitcnt lgkmcnt(" #n ")" ::: "memory")
; #define PG8_BAR __builtin_amdgcn_s_barrier()
; #define PG8_SCHED __builtin_amdgcn_sched_barrier(0)
; template <class Epi, class Sched, bool ALIGN_EPI = false, bool SP2 = false>
; __device__ __forceinline__ void gemm_phase(PG8_LAS unsigned char* lds, const Gemm g, const Sched& S, const Epi& E, const int tid_) {
;     ...
;         for (int t = 0; t < nt; t += 2) {
;     ...
;             PG8_LDA(At, 1, 1); PG8_STAGE(PG8_SB(1, 0), b3, voffB); PG8_STAGE(PG8_SB(1, 1), b3 + hstepB, voffB); PG8_STAGE(PG8_SA(1, 0), a3, voffA);
;             PG8_WAIT_V(8); PG8_WAIT_L(0); PG8_BAR; PG8_MMA(1, 0, At, B0); PG8_MMA(1, 1, At, B1); PG8_BAR; PG8_SCHED;
	s_mov_b32 m0, s64
	v_lshl_add_u64 v[212:213], v[212:213], 0, s[96:97]
	ds_read_b128 v[164:167], v216 offset:49152
	ds_read_b128 v[168:171], v216 offset:50176
	ds_read_b128 v[172:175], v216 offset:51200
	ds_read_b128 v[176:179], v216 offset:52224
	ds_read_b128 v[196:199], v216 offset:53248
	ds_read_b128 v[200:203], v216 offset:54272
	ds_read_b128 v[204:207], v216 offset:55296
	ds_read_b128 v[208:211], v216 offset:56320
	global_load_lds_dwordx4 v[212:213], off
	v_lshl_add_u64 v[212:213], v[218:219], 0, s[96:97]
	s_mov_b32 m0, s65
	s_nop 0
	global_load_lds_dwordx4 v[212:213], off
	v_lshl_add_u64 v[212:213], v[220:221], 0, s[96:97]
	s_mov_b32 m0, s69
	s_nop 0
	global_load_lds_dwordx4 v[212:213], off
	v_lshl_add_u64 v[212:213], v[222:223], 0, s[96:97]
	s_mov_b32 m0, s70
	s_nop 0
	global_load_lds_dwordx4 v[212:213], off
	v_lshl_add_u64 v[212:213], v[224:225], 0, s[96:97]
	s_mov_b32 m0, s66
	s_nop 0
	global_load_lds_dwordx4 v[212:213], off
	v_lshl_add_u64 v[212:213], v[226:227], 0, s[96:97]
	s_mov_b32 m0, s67
	s_nop 0
	global_load_lds_dwordx4 v[212:213], off
	s_waitcnt vmcnt(8)
	s_waitcnt lgkmcnt(0)
	s_barrier
	s_setprio 1
	s_waitcnt lgkmcnt(0)
	v_mfma_f32_16x16x32_bf16 v[80:83], v[52:55], v[164:167], v[80:83]
	v_mfma_f32_16x16x32_bf16 v[76:79], v[68:71], v[164:167], v[76:79]
	v_mfma_f32_16x16x32_bf16 v[64:67], v[52:55], v[172:175], v[64:67]
	v_mfma_f32_16x16x32_bf16 v[60:63], v[68:71], v[172:175], v[60:63]
	v_mfma_f32_16x16x32_bf16 v[32:35], v[52:55], v[196:199], v[32:35]
	v_mfma_f32_16x16x32_bf16 v[28:31], v[68:71], v[196:199], v[28:31]
	v_mfma_f32_16x16x32_bf16 v[16:19], v[52:55], v[204:207], v[16:19]
	v_mfma_f32_16x16x32_bf16 v[12:15], v[68:71], v[204:207], v[12:15]
	v_mfma_f32_16x16x32_bf16 v[80:83], v[56:59], v[168:171], v[80:83]
	v_mfma_f32_16x16x32_bf16 v[76:79], v[72:75], v[168:171], v[76:79]
	v_mfma_f32_16x16x32_bf16 v[64:67], v[56:59], v[176:179], v[64:67]
	v_mfma_f32_16x16x32_bf16 v[60:63], v[72:75], v[176:179], v[60:63]
	v_mfma_f32_16x16x32_bf16 v[32:35], v[56:59], v[200:203], v[32:35]
	v_mfma_f32_16x16x32_bf16 v[28:31], v[72:75], v[200:203], v[28:31]
	v_mfma_f32_16x16x32_bf16 v[16:19], v[56:59], v[208:211], v[16:19]
	v_mfma_f32_16x16x32_bf16 v[12:15], v[72:75], v[208:211], v[12:15]
	s_setprio 0
	s_setprio 1
	v_mfma_f32_16x16x32_bf16 v[36:39], v[148:151], v[164:167], v[36:39]
	v_mfma_f32_16x16x32_bf16 v[72:75], v[152:155], v[168:171], v[36:39]
	v_mfma_f32_16x16x32_bf16 v[36:39], v[156:159], v[164:167], v[40:43]
	v_mfma_f32_16x16x32_bf16 v[68:71], v[160:163], v[168:171], v[36:39]
	v_mfma_f32_16x16x32_bf16 v[36:39], v[148:151], v[172:175], v[48:51]
	v_mfma_f32_16x16x32_bf16 v[52:55], v[152:155], v[176:179], v[36:39]
	v_mfma_f32_16x16x32_bf16 v[36:39], v[156:159], v[172:175], v[44:47]
	v_mfma_f32_16x16x32_bf16 v[24:27], v[148:151], v[196:199], v[24:27]
	v_mfma_f32_16x16x32_bf16 v[20:23], v[156:159], v[196:199], v[20:23]
	v_mfma_f32_16x16x32_bf16 v[8:11], v[148:151], v[204:207], v[8:11]
	v_mfma_f32_16x16x32_bf16 v[4:7], v[156:159], v[204:207], v[4:7]
	v_mfma_f32_16x16x32_bf16 v[44:47], v[160:163], v[176:179], v[36:39]
	v_mfma_f32_16x16x32_bf16 v[24:27], v[152:155], v[200:203], v[24:27]
	v_mfma_f32_16x16x32_bf16 v[20:23], v[160:163], v[200:203], v[20:23]
	v_mfma_f32_16x16x32_bf16 v[8:11], v[152:155], v[208:211], v[8:11]
	v_mfma_f32_16x16x32_bf16 v[4:7], v[160:163], v[208:211], v[4:7]
	s_setprio 0
	s_barrier
	s_add_u32 s12, s12, 0x100
	s_addc_u32 s13, s13, 0
	s_add_u32 s2, s2, 0x100
	s_addc_u32 s3, s3, 0
	s_cmp_ge_u32 s46, s73
	s_mov_b32 s14, s46
